# code placement: the three GEMM main loops shifted by 4 bytes so that every 8-byte MFMA sits at 0 mod 8 (pads before the loop head and behind the back edge)
# speedup vs baseline: 1.0113x; 1.0113x over previous
; #define PG8_WAIT_V(n) asm volatile("s_waitcnt vmcnt(" #n ")" ::: "memory")
; template <class Epi, bool ALIGN_EPI, bool SP2, bool BF = false, bool HALFM = false, class Order = StaticOrder>
; __device__ __forceinline__ void gemm_phase(LAS unsigned char* lds, const int tid, const Gemm g, const Order& S, const Epi& E, const bool dry = false) {
;     ...
;     Unit cur, nxt; int ui = 0;
;     if (!S.next(0, cur)) return;
;     f32x4 acc[2][2][4][2];
; #pragma unroll
;     for (int a = 0; a < 2; ++a)
; #pragma unroll
;         for (int b = 0; b < 2; ++b)
; #pragma unroll
;             for (int m = 0; m < 4; ++m)
; #pragma unroll
;                 for (int n = 0; n < 2; ++n) acc[a][b][m][n] = (f32x4){0.f, 0.f, 0.f, 0.f};
;     h16x8 At[4][2], B0[2][2], B1[2][2];
;     const char* cA = (const char*)g.A + (size_t)cur.pm * tstep + (HALFM ? (size_t)cur.hm * hstep : (size_t)0); const char* cB = (const char*)g.Bt + (size_t)cur.pn * tstep;
;     if constexpr (SP2) {
;         PG8_STAGE(PG8_SB(0, 0), cB); PG8_STAGE(PG8_SB(0, 1), cB + hstep); PG8_STAGE(PG8_SA(0, 0), cA); PG8_STAGE(PG8_SA(0, 1), cA + hstep);
;         if (wr == 1) PG8_BAR;
;         PG8_WAIT_V(2); PG8_BAR;
;         PG8_STAGE(PG8_SB(1, 0), cB + kstep); PG8_STAGE(PG8_SA(1, 0), cA + kstep); PG8_STAGE(PG8_SB(1, 1), cB + hstep + kstep);
;         PG8_WAIT_V(6); PG8_BAR;
;     } else {
;         PG8_STAGE(PG8_SB(0, 0), cB); PG8_STAGE(PG8_SA(0, 0), cA); PG8_STAGE(PG8_SB(0, 1), cB + hstep); PG8_STAGE(PG8_SA(0, 1), cA + hstep);
;         if (wr == 1) PG8_BAR;
;         PG8_WAIT_V(4); PG8_BAR;
;         PG8_STAGE(PG8_SB(1, 0), cB + kstep); PG8_STAGE(PG8_SA(1, 0), cA + kstep); PG8_STAGE(PG8_SB(1, 1), cB + hstep + kstep);
;         PG8_WAIT_V(6); PG8_BAR;
;     }
;     for (;;) {
;         const bool has_next = S.next(ui + 1, nxt);
;         const char* nA = has_next ? (const char*)g.A + (size_t)nxt.pm * tstep + (HALFM ? (size_t)nxt.hm * hstep : (size_t)0) : cA; const char* nB = has_next ? (const char*)g.Bt + (size_t)nxt.pn * tstep : cB;
;         for (int t = 0; t < nt; t += 2) {
;             const bool last = (t == nt - 2);
;             const char* a1 = cA + (size_t)(t + 1) * kstep;
;             const char* a2 = last ? nA : cA + (size_t)(t + 2) * kstep; const char* b2 = last ? nB : cB + (size_t)(t + 2) * kstep;
;             const char* a3 = a2 + kstep; const char* b3 = b2 + kstep;
;             if constexpr (SP2) {
.LBB0_451:
	s_ashr_i32 s21, s20, 31
	s_lshl_b64 s[22:23], s[20:21], 19
	v_readlane_b32 s56, v251, 0
	v_readlane_b32 s57, v251, 1
	s_add_u32 s22, s56, s22
	s_addc_u32 s23, s57, s23
	s_and_b64 s[24:25], s[36:37], exec
	s_cselect_b32 s1, s23, s3
	s_cselect_b32 s5, s22, s2
	s_ashr_i32 s19, s18, 31
	s_lshl_b64 s[24:25], s[18:19], 19
	s_add_u32 s24, s49, s24
	s_addc_u32 s25, s50, s25
	s_and_b64 s[42:43], s[36:37], exec
	s_cselect_b32 s19, s25, s39
	s_cselect_b32 s21, s24, s38
	s_add_u32 s2, s2, 0x40080
	s_addc_u32 s3, s3, 0
	s_add_u32 s44, s38, 0x100
	v_mov_b32_e32 v2, 0
	s_addc_u32 s45, s39, 0
	s_mov_b32 s97, -2
	v_mov_b32_e32 v3, v2
	v_mov_b32_e32 v4, v2
	v_mov_b32_e32 v5, v2
	v_mov_b32_e32 v6, v2
	v_mov_b32_e32 v7, v2
	v_mov_b32_e32 v8, v2
	v_mov_b32_e32 v9, v2
	v_mov_b32_e32 v34, v2
	v_mov_b32_e32 v35, v2
	v_mov_b32_e32 v36, v2
	v_mov_b32_e32 v37, v2
	v_mov_b32_e32 v38, v2
	v_mov_b32_e32 v39, v2
	v_mov_b32_e32 v40, v2
	v_mov_b32_e32 v41, v2
	s_waitcnt vmcnt(0)
	v_mov_b32_e32 v66, v2
	v_mov_b32_e32 v67, v2
	v_mov_b32_e32 v68, v2
	v_mov_b32_e32 v69, v2
	v_mov_b32_e32 v70, v2
	v_mov_b32_e32 v71, v2
	v_mov_b32_e32 v72, v2
	v_mov_b32_e32 v73, v2
	v_mov_b32_e32 v82, v2
	v_mov_b32_e32 v83, v2
	v_mov_b32_e32 v84, v2
	v_mov_b32_e32 v85, v2
	v_mov_b32_e32 v86, v2
	v_mov_b32_e32 v87, v2
	v_mov_b32_e32 v88, v2
	v_mov_b32_e32 v89, v2
	v_mov_b32_e32 v10, v2
	v_mov_b32_e32 v11, v2
	v_mov_b32_e32 v12, v2
	v_mov_b32_e32 v13, v2
	v_mov_b32_e32 v14, v2
	v_mov_b32_e32 v15, v2
	v_mov_b32_e32 v16, v2
	v_mov_b32_e32 v17, v2
	v_mov_b32_e32 v42, v2
	v_mov_b32_e32 v43, v2
	v_mov_b32_e32 v44, v2
	v_mov_b32_e32 v45, v2
	v_mov_b32_e32 v46, v2
	v_mov_b32_e32 v47, v2
	v_mov_b32_e32 v48, v2
	v_mov_b32_e32 v49, v2
	v_mov_b32_e32 v74, v2
	v_mov_b32_e32 v75, v2
	v_mov_b32_e32 v76, v2
	v_mov_b32_e32 v77, v2
	v_mov_b32_e32 v78, v2
	v_mov_b32_e32 v79, v2
	v_mov_b32_e32 v80, v2
	v_mov_b32_e32 v81, v2
	v_mov_b32_e32 v90, v2
	v_mov_b32_e32 v91, v2
	v_mov_b32_e32 v92, v2
	v_mov_b32_e32 v93, v2
	v_mov_b32_e32 v94, v2
	v_mov_b32_e32 v95, v2
	v_mov_b32_e32 v96, v2
	v_mov_b32_e32 v97, v2
	v_mov_b32_e32 v98, v2
	v_mov_b32_e32 v99, v2
	v_mov_b32_e32 v100, v2
	v_mov_b32_e32 v101, v2
	v_mov_b32_e32 v102, v2
	v_mov_b32_e32 v103, v2
	v_mov_b32_e32 v104, v2
	v_mov_b32_e32 v105, v2
	v_mov_b32_e32 v114, v2
	v_mov_b32_e32 v115, v2
	v_mov_b32_e32 v116, v2
	v_mov_b32_e32 v117, v2
	v_mov_b32_e32 v118, v2
	v_mov_b32_e32 v119, v2
	v_mov_b32_e32 v120, v2
	v_mov_b32_e32 v121, v2
	v_mov_b32_e32 v132, v2
	v_mov_b32_e32 v133, v2
	v_mov_b32_e32 v134, v2
	v_mov_b32_e32 v135, v2
	v_mov_b32_e32 v136, v2
	v_mov_b32_e32 v137, v2
	v_mov_b32_e32 v138, v2
	v_mov_b32_e32 v139, v2
	v_mov_b32_e32 v148, v2
	v_mov_b32_e32 v149, v2
	v_mov_b32_e32 v150, v2
	v_mov_b32_e32 v151, v2
	v_mov_b32_e32 v152, v2
	v_mov_b32_e32 v153, v2
	v_mov_b32_e32 v154, v2
	v_mov_b32_e32 v155, v2
	v_mov_b32_e32 v106, v2
	v_mov_b32_e32 v107, v2
	v_mov_b32_e32 v108, v2
	v_mov_b32_e32 v109, v2
	v_mov_b32_e32 v110, v2
	v_mov_b32_e32 v111, v2
	v_mov_b32_e32 v112, v2
	v_mov_b32_e32 v113, v2
	v_mov_b32_e32 v122, v2
	v_mov_b32_e32 v123, v2
	v_mov_b32_e32 v124, v2
	v_mov_b32_e32 v125, v2
	v_mov_b32_e32 v126, v2
	v_mov_b32_e32 v127, v2
	v_mov_b32_e32 v128, v2
	v_mov_b32_e32 v129, v2
	v_mov_b32_e32 v140, v2
	v_mov_b32_e32 v141, v2
	v_mov_b32_e32 v142, v2
	v_mov_b32_e32 v143, v2
	v_mov_b32_e32 v144, v2
	v_mov_b32_e32 v145, v2
	v_mov_b32_e32 v146, v2
	v_mov_b32_e32 v147, v2
	v_mov_b32_e32 v156, v2
	v_mov_b32_e32 v157, v2
	v_mov_b32_e32 v158, v2
	v_mov_b32_e32 v159, v2
	v_mov_b32_e32 v160, v2
	v_mov_b32_e32 v161, v2
	v_mov_b32_e32 v162, v2
	v_mov_b32_e32 v163, v2
	v_readlane_b32 s58, v251, 2
	v_readlane_b32 s59, v251, 3
	v_readlane_b32 s60, v251, 4
	v_readlane_b32 s61, v251, 5
	v_readlane_b32 s62, v251, 6
	v_readlane_b32 s63, v251, 7
	s_nop 0
.LBB0_452:
	v_add_u32_e32 v0, s52, v189
	ds_read_b128 v[18:21], v0
	ds_read_b128 v[22:25], v0 offset:1024
	ds_read_b128 v[26:29], v0 offset:2048
	ds_read_b128 v[30:33], v0 offset:3072
	v_add_u32_e32 v0, s55, v189
	ds_read_b128 v[50:53], v0
	ds_read_b128 v[54:57], v0 offset:1024
	ds_read_b128 v[58:61], v0 offset:2048
	ds_read_b128 v[62:65], v0 offset:3072
	s_add_u32 s38, s2, 0xfffc0080
	s_addc_u32 s39, s3, -1
	s_cmp_eq_u32 s97, 12
	s_cselect_b32 s43, s1, s39
	s_cselect_b32 s42, s5, s38
	s_cselect_b32 s39, s19, s45
	s_cselect_b32 s38, s21, s44
	v_lshl_add_u64 v[222:223], s[2:3], 0, v[168:169]
	s_add_i32 m0, s79, 0xc000
	ds_read_b128 v[172:175], v190
	ds_read_b128 v[176:179], v190 offset:1024
	ds_read_b128 v[192:195], v190 offset:2048
	ds_read_b128 v[196:199], v190 offset:3072
	ds_read_b128 v[200:203], v190 offset:4096
	ds_read_b128 v[204:207], v190 offset:5120
	ds_read_b128 v[214:217], v190 offset:6144
	ds_read_b128 v[218:221], v190 offset:7168
	global_load_lds_dwordx4 v[222:223], off
	v_lshl_add_u64 v[222:223], s[2:3], 0, v[170:171]
	s_add_i32 m0, s79, 0xe000
	s_nop 0
	global_load_lds_dwordx4 v[222:223], off
	s_waitcnt vmcnt(8)
	s_waitcnt lgkmcnt(0)
	s_barrier
; #define PG8_STAGE(bufoff, gbase) do { _Pragma("unroll") for (int _i = 0; _i < 2; ++_i) \
;         __builtin_amdgcn_global_load_lds((const unsigned*)((const char*)(gbase) + voffA[_i]), (LAS unsigned*)(lds + (bufoff) + ldsw + _i * 8192), 16, 0, 0); } while (0)
; #define PG8_LDA1(dst, b) do { if constexpr (!HALFM) PG8_LDA(dst, b, 1); } while (0)
; #define PG8_MMA1(At, B0, B1) do { if constexpr (!HALFM) { PG8_MMA(1, 0, At, B0); PG8_MMA(1, 1, At, B1); } } while (0)
; #define PG8_WAIT_V(n) asm volatile("s_waitcnt vmcnt(" #n ")" ::: "memory")
; #define PG8_WAIT_L(n) asm volatile("s_waitcnt lgkmcnt(" #n ")" ::: "memory")
; #define PG8_BAR __builtin_amdgcn_s_barrier()
; #define PG8_SCHED __builtin_amdgcn_sched_barrier(0)
; template <class Epi, bool ALIGN_EPI, bool SP2, bool BF = false, bool HALFM = false, class Order = StaticOrder>
; __device__ __forceinline__ void gemm_phase(LAS unsigned char* lds, const int tid, const Gemm g, const Order& S, const Epi& E, const bool dry = false) {
;     ...
;             PG8_WAIT_V(8); PG8_WAIT_L(0); PG8_BAR; PG8_MMA(0, 0, At, B0); PG8_MMA(0, 1, At, B1); PG8_BAR; PG8_SCHED;
;             PG8_LDA1(At, 0); PG8_STAGE(PG8_SB(0, 0), b2); PG8_STAGE(PG8_SB(0, 1), b2 + hstep); PG8_STAGE(PG8_SA(0, 0), a2);
;             PG8_WAIT_V(8); PG8_WAIT_L(0); PG8_BAR; PG8_MMA1(At, B0, B1); PG8_BAR; PG8_SCHED;
	s_waitcnt lgkmcnt(0)
	v_mfma_f32_16x16x32_f16 v[160:163], v[18:21], v[172:175], v[160:163]
	v_mfma_f32_16x16x32_f16 v[156:159], v[26:29], v[172:175], v[156:159]
	v_mfma_f32_16x16x32_f16 v[144:147], v[18:21], v[192:195], v[144:147]
	v_mfma_f32_16x16x32_f16 v[140:143], v[26:29], v[192:195], v[140:143]
	v_mfma_f32_16x16x32_f16 v[126:129], v[18:21], v[200:203], v[126:129]
	v_mfma_f32_16x16x32_f16 v[122:125], v[26:29], v[200:203], v[122:125]
	v_mfma_f32_16x16x32_f16 v[110:113], v[18:21], v[214:217], v[110:113]
	v_mfma_f32_16x16x32_f16 v[106:109], v[26:29], v[214:217], v[106:109]
	v_mfma_f32_16x16x32_f16 v[160:163], v[22:25], v[176:179], v[160:163]
	v_mfma_f32_16x16x32_f16 v[156:159], v[30:33], v[176:179], v[156:159]
	v_mfma_f32_16x16x32_f16 v[144:147], v[22:25], v[196:199], v[144:147]
	v_mfma_f32_16x16x32_f16 v[140:143], v[30:33], v[196:199], v[140:143]
	v_mfma_f32_16x16x32_f16 v[126:129], v[22:25], v[204:207], v[126:129]
	v_mfma_f32_16x16x32_f16 v[122:125], v[30:33], v[204:207], v[122:125]
	v_mfma_f32_16x16x32_f16 v[110:113], v[22:25], v[218:221], v[110:113]
	v_mfma_f32_16x16x32_f16 v[106:109], v[30:33], v[218:221], v[106:109]
	v_mfma_f32_16x16x32_f16 v[152:155], v[50:53], v[172:175], v[152:155]
	v_mfma_f32_16x16x32_f16 v[148:151], v[58:61], v[172:175], v[148:151]
	v_mfma_f32_16x16x32_f16 v[136:139], v[50:53], v[192:195], v[136:139]
	v_mfma_f32_16x16x32_f16 v[132:135], v[58:61], v[192:195], v[132:135]
	v_mfma_f32_16x16x32_f16 v[118:121], v[50:53], v[200:203], v[118:121]
	v_mfma_f32_16x16x32_f16 v[114:117], v[58:61], v[200:203], v[114:117]
	v_mfma_f32_16x16x32_f16 v[102:105], v[50:53], v[214:217], v[102:105]
	v_mfma_f32_16x16x32_f16 v[98:101], v[58:61], v[214:217], v[98:101]
	v_mfma_f32_16x16x32_f16 v[152:155], v[54:57], v[176:179], v[152:155]
	v_mfma_f32_16x16x32_f16 v[148:151], v[62:65], v[176:179], v[148:151]
	v_mfma_f32_16x16x32_f16 v[136:139], v[54:57], v[196:199], v[136:139]
	v_mfma_f32_16x16x32_f16 v[132:135], v[62:65], v[196:199], v[132:135]
	v_mfma_f32_16x16x32_f16 v[118:121], v[54:57], v[204:207], v[118:121]
	v_mfma_f32_16x16x32_f16 v[114:117], v[62:65], v[204:207], v[114:117]
	v_mfma_f32_16x16x32_f16 v[102:105], v[54:57], v[218:221], v[102:105]
	v_mfma_f32_16x16x32_f16 v[98:101], v[62:65], v[218:221], v[98:101]
	s_barrier
	s_mov_b32 m0, s53
	v_lshl_add_u64 v[226:227], s[38:39], 0, v[164:165]
	s_add_u32 vcc_lo, s38, 0x40000
	ds_read_b128 v[172:175], v190 offset:16384
	ds_read_b128 v[176:179], v190 offset:17408
	ds_read_b128 v[192:195], v190 offset:18432
	ds_read_b128 v[196:199], v190 offset:19456
	ds_read_b128 v[200:203], v190 offset:20480
	ds_read_b128 v[204:207], v190 offset:21504
	ds_read_b128 v[214:217], v190 offset:22528
	ds_read_b128 v[218:221], v190 offset:23552
	global_load_lds_dwordx4 v[226:227], off
	v_lshl_add_u64 v[238:239], s[38:39], 0, v[166:167]
	s_mov_b32 m0, s54
	s_addc_u32 vcc_hi, s39, 0
	global_load_lds_dwordx4 v[238:239], off
	v_lshl_add_u64 v[222:223], vcc, 0, v[164:165]
	s_mov_b32 m0, s77
	v_lshl_add_u64 v[248:249], s[42:43], 0, v[164:165]
	global_load_lds_dwordx4 v[222:223], off
	v_lshl_add_u64 v[222:223], vcc, 0, v[166:167]
	s_mov_b32 m0, s78
	v_lshl_add_u64 v[210:211], s[42:43], 0, v[166:167]
	global_load_lds_dwordx4 v[222:223], off
	s_mov_b32 m0, s79
	s_nop 0
	global_load_lds_dwordx4 v[248:249], off
	s_mov_b32 m0, s80
	s_nop 0
	global_load_lds_dwordx4 v[210:211], off
	s_waitcnt vmcnt(8)
	s_waitcnt lgkmcnt(0)
	s_barrier
	s_waitcnt lgkmcnt(0)
	v_mfma_f32_16x16x32_f16 v[94:97], v[18:21], v[172:175], v[94:97]
	v_mfma_f32_16x16x32_f16 v[90:93], v[26:29], v[172:175], v[90:93]
	v_mfma_f32_16x16x32_f16 v[78:81], v[18:21], v[192:195], v[78:81]
	v_mfma_f32_16x16x32_f16 v[74:77], v[26:29], v[192:195], v[74:77]
	v_mfma_f32_16x16x32_f16 v[46:49], v[18:21], v[200:203], v[46:49]
	v_mfma_f32_16x16x32_f16 v[42:45], v[26:29], v[200:203], v[42:45]
	v_mfma_f32_16x16x32_f16 v[14:17], v[18:21], v[214:217], v[14:17]
	v_mfma_f32_16x16x32_f16 v[10:13], v[26:29], v[214:217], v[10:13]
	v_mfma_f32_16x16x32_f16 v[94:97], v[22:25], v[176:179], v[94:97]
	v_mfma_f32_16x16x32_f16 v[90:93], v[30:33], v[176:179], v[90:93]
	v_mfma_f32_16x16x32_f16 v[78:81], v[22:25], v[196:199], v[78:81]
	v_mfma_f32_16x16x32_f16 v[74:77], v[30:33], v[196:199], v[74:77]
	v_mfma_f32_16x16x32_f16 v[46:49], v[22:25], v[204:207], v[46:49]
	v_mfma_f32_16x16x32_f16 v[42:45], v[30:33], v[204:207], v[42:45]
	v_mfma_f32_16x16x32_f16 v[14:17], v[22:25], v[218:221], v[14:17]
	v_mfma_f32_16x16x32_f16 v[10:13], v[30:33], v[218:221], v[10:13]
	v_mfma_f32_16x16x32_f16 v[38:41], v[50:53], v[200:203], v[38:41]
	v_mfma_f32_16x16x32_f16 v[34:37], v[58:61], v[200:203], v[34:37]
	v_mfma_f32_16x16x32_f16 v[6:9], v[50:53], v[214:217], v[6:9]
	v_mfma_f32_16x16x32_f16 v[2:5], v[58:61], v[214:217], v[2:5]
	v_mfma_f32_16x16x32_f16 v[18:21], v[50:53], v[172:175], v[86:89]
	v_mfma_f32_16x16x32_f16 v[22:25], v[58:61], v[172:175], v[82:85]
	v_mfma_f32_16x16x32_f16 v[26:29], v[50:53], v[192:195], v[70:73]
	v_mfma_f32_16x16x32_f16 v[30:33], v[58:61], v[192:195], v[66:69]
	v_mfma_f32_16x16x32_f16 v[38:41], v[54:57], v[204:207], v[38:41]
	v_mfma_f32_16x16x32_f16 v[34:37], v[62:65], v[204:207], v[34:37]
	v_mfma_f32_16x16x32_f16 v[6:9], v[54:57], v[218:221], v[6:9]
	v_mfma_f32_16x16x32_f16 v[2:5], v[62:65], v[218:221], v[2:5]
	v_mfma_f32_16x16x32_f16 v[18:21], v[54:57], v[176:179], v[18:21]
	v_mfma_f32_16x16x32_f16 v[22:25], v[62:65], v[176:179], v[22:25]
	v_mfma_f32_16x16x32_f16 v[26:29], v[54:57], v[196:199], v[26:29]
	v_mfma_f32_16x16x32_f16 v[30:33], v[62:65], v[196:199], v[30:33]
	s_barrier
; #define PG8_STAGE(bufoff, gbase) do { _Pragma("unroll") for (int _i = 0; _i < 2; ++_i) \
;         __builtin_amdgcn_global_load_lds((const unsigned*)((const char*)(gbase) + voffA[_i]), (LAS unsigned*)(lds + (bufoff) + ldsw + _i * 8192), 16, 0, 0); } while (0)
; #define PG8_LDA(dst, b, h) do { _Pragma("unroll") for (int m = 0; m < 4; ++m) _Pragma("unroll") for (int k = 0; k < 2; ++k) dst[m][k] = *(const LAS h16x8*)(lds + PG8_SA(b, h) + aoff + m * 2048 + k * 1024); } while (0)
; #define PG8_LDB(dst, b, h) do { _Pragma("unroll") for (int n = 0; n < 2; ++n) _Pragma("unroll") for (int k = 0; k < 2; ++k) dst[n][k] = *(const LAS h16x8*)(lds + PG8_SB(b, h) + boff + n * 2048 + k * 1024); } while (0)
; #define PG8_LDA1(dst, b) do { if constexpr (!HALFM) PG8_LDA(dst, b, 1); } while (0)
; #define PG8_MMA1(At, B0, B1) do { if constexpr (!HALFM) { PG8_MMA(1, 0, At, B0); PG8_MMA(1, 1, At, B1); } } while (0)
; #define PG8_WAIT_V(n) asm volatile("s_waitcnt vmcnt(" #n ")" ::: "memory")
; #define PG8_WAIT_L(n) asm volatile("s_waitcnt lgkmcnt(" #n ")" ::: "memory")
; #define PG8_BAR __builtin_amdgcn_s_barrier()
; #define PG8_SCHED __builtin_amdgcn_sched_barrier(0)
; template <class Epi, bool ALIGN_EPI, bool SP2, bool BF = false, bool HALFM = false, class Order = StaticOrder>
; __device__ __forceinline__ void gemm_phase(LAS unsigned char* lds, const int tid, const Gemm g, const Order& S, const Epi& E, const bool dry = false) {
;     ...
;             PG8_LDB(B0, 1, 0); PG8_LDB(B1, 1, 1); PG8_SCHED; PG8_LDA(At, 1, 0); PG8_STAGE(PG8_SA(0, 1), a2 + hstep);
;             PG8_WAIT_V(8); PG8_WAIT_L(0); PG8_BAR; PG8_MMA(0, 0, At, B0); PG8_MMA(0, 1, At, B1); PG8_BAR; PG8_SCHED;
;             PG8_LDA1(At, 1); PG8_STAGE(PG8_SB(1, 0), b3); PG8_STAGE(PG8_SB(1, 1), b3 + hstep); PG8_STAGE(PG8_SA(1, 0), a3);
;             PG8_WAIT_V(8); PG8_WAIT_L(0); PG8_BAR; PG8_MMA1(At, B0, B1); PG8_BAR; PG8_SCHED;
;     ...
;         if constexpr (ALIGN_EPI) { if (wr == 0) PG8_BAR; }
	v_add_u32_e32 v0, s85, v189
	ds_read_b128 v[50:53], v0
	ds_read_b128 v[54:57], v0 offset:1024
	ds_read_b128 v[58:61], v0 offset:2048
	ds_read_b128 v[62:65], v0 offset:3072
	v_add_u32_e32 v0, s51, v189
	ds_read_b128 v[172:175], v0
	ds_read_b128 v[176:179], v0 offset:1024
	ds_read_b128 v[192:195], v0 offset:2048
	ds_read_b128 v[196:199], v0 offset:3072
	s_add_u32 s42, s42, 0x40000
	s_addc_u32 s43, s43, 0
	s_mov_b32 m0, s81
	v_lshl_add_u64 v[222:223], s[42:43], 0, v[164:165]
	ds_read_b128 v[66:69], v190 offset:32768
	ds_read_b128 v[70:73], v190 offset:33792
	ds_read_b128 v[82:85], v190 offset:34816
	ds_read_b128 v[86:89], v190 offset:35840
	ds_read_b128 v[200:203], v190 offset:36864
	ds_read_b128 v[204:207], v190 offset:37888
	ds_read_b128 v[214:217], v190 offset:38912
	ds_read_b128 v[218:221], v190 offset:39936
	global_load_lds_dwordx4 v[222:223], off
	v_lshl_add_u64 v[222:223], s[42:43], 0, v[166:167]
	s_mov_b32 m0, s82
	s_nop 0
	global_load_lds_dwordx4 v[222:223], off
	s_waitcnt vmcnt(8)
	s_waitcnt lgkmcnt(0)
	s_barrier
	s_waitcnt lgkmcnt(0)
	v_mfma_f32_16x16x32_f16 v[160:163], v[50:53], v[66:69], v[160:163]
	v_mfma_f32_16x16x32_f16 v[156:159], v[58:61], v[66:69], v[156:159]
	v_mfma_f32_16x16x32_f16 v[144:147], v[50:53], v[82:85], v[144:147]
	v_mfma_f32_16x16x32_f16 v[140:143], v[58:61], v[82:85], v[140:143]
	v_mfma_f32_16x16x32_f16 v[126:129], v[50:53], v[200:203], v[126:129]
	v_mfma_f32_16x16x32_f16 v[122:125], v[58:61], v[200:203], v[122:125]
	v_mfma_f32_16x16x32_f16 v[110:113], v[50:53], v[214:217], v[110:113]
	v_mfma_f32_16x16x32_f16 v[106:109], v[58:61], v[214:217], v[106:109]
	v_mfma_f32_16x16x32_f16 v[160:163], v[54:57], v[70:73], v[160:163]
	v_mfma_f32_16x16x32_f16 v[156:159], v[62:65], v[70:73], v[156:159]
	v_mfma_f32_16x16x32_f16 v[144:147], v[54:57], v[86:89], v[144:147]
	v_mfma_f32_16x16x32_f16 v[140:143], v[62:65], v[86:89], v[140:143]
	v_mfma_f32_16x16x32_f16 v[126:129], v[54:57], v[204:207], v[126:129]
	v_mfma_f32_16x16x32_f16 v[122:125], v[62:65], v[204:207], v[122:125]
	v_mfma_f32_16x16x32_f16 v[110:113], v[54:57], v[218:221], v[110:113]
	v_mfma_f32_16x16x32_f16 v[106:109], v[62:65], v[218:221], v[106:109]
	v_mfma_f32_16x16x32_f16 v[152:155], v[172:175], v[66:69], v[152:155]
	v_mfma_f32_16x16x32_f16 v[66:69], v[192:195], v[66:69], v[148:151]
	v_mfma_f32_16x16x32_f16 v[148:151], v[196:199], v[70:73], v[66:69]
	v_mfma_f32_16x16x32_f16 v[66:69], v[172:175], v[82:85], v[136:139]
	v_mfma_f32_16x16x32_f16 v[136:139], v[176:179], v[86:89], v[66:69]
	v_mfma_f32_16x16x32_f16 v[66:69], v[192:195], v[82:85], v[132:135]
	v_mfma_f32_16x16x32_f16 v[132:135], v[196:199], v[86:89], v[66:69]
	v_mfma_f32_16x16x32_f16 v[66:69], v[172:175], v[200:203], v[118:121]
	v_mfma_f32_16x16x32_f16 v[118:121], v[176:179], v[204:207], v[66:69]
	v_mfma_f32_16x16x32_f16 v[66:69], v[192:195], v[200:203], v[114:117]
	v_mfma_f32_16x16x32_f16 v[114:117], v[196:199], v[204:207], v[66:69]
	v_mfma_f32_16x16x32_f16 v[66:69], v[172:175], v[214:217], v[102:105]
	v_mfma_f32_16x16x32_f16 v[102:105], v[176:179], v[218:221], v[66:69]
	v_mfma_f32_16x16x32_f16 v[66:69], v[192:195], v[214:217], v[98:101]
	v_mfma_f32_16x16x32_f16 v[152:155], v[176:179], v[70:73], v[152:155]
	v_mfma_f32_16x16x32_f16 v[98:101], v[196:199], v[218:221], v[66:69]
	s_barrier
	s_mov_b32 m0, s86
	v_lshl_add_u64 v[82:83], v[226:227], 0, s[94:95]
	s_add_u32 s38, s38, 0x40080
	s_nop 0
	ds_read_b128 v[66:69], v190 offset:49152
	ds_read_b128 v[70:73], v190 offset:50176
	ds_read_b128 v[200:203], v190 offset:51200
	ds_read_b128 v[204:207], v190 offset:52224
	ds_read_b128 v[214:217], v190 offset:53248
	ds_read_b128 v[218:221], v190 offset:54272
	ds_read_b128 v[222:225], v190 offset:55296
	ds_read_b128 v[230:233], v190 offset:56320
	global_load_lds_dwordx4 v[82:83], off
	v_lshl_add_u64 v[82:83], v[238:239], 0, s[94:95]
	s_mov_b32 m0, s87
	s_addc_u32 s39, s39, 0
	global_load_lds_dwordx4 v[82:83], off
	v_lshl_add_u64 v[82:83], s[38:39], 0, v[164:165]
	s_mov_b32 m0, s8
	s_nop 0
	global_load_lds_dwordx4 v[82:83], off
	v_lshl_add_u64 v[82:83], s[38:39], 0, v[166:167]
	s_mov_b32 m0, s9
	s_nop 0
	global_load_lds_dwordx4 v[82:83], off
	v_lshl_add_u64 v[82:83], v[248:249], 0, s[94:95]
	s_mov_b32 m0, s76
	s_nop 0
	global_load_lds_dwordx4 v[82:83], off
	v_lshl_add_u64 v[82:83], v[210:211], 0, s[94:95]
	s_mov_b32 m0, s48
	s_nop 0
	global_load_lds_dwordx4 v[82:83], off
	s_waitcnt vmcnt(8)
	s_waitcnt lgkmcnt(0)
	s_barrier
	s_waitcnt lgkmcnt(0)
	v_mfma_f32_16x16x32_f16 v[82:85], v[50:53], v[66:69], v[94:97]
	v_mfma_f32_16x16x32_f16 v[94:97], v[54:57], v[70:73], v[82:85]
	v_mfma_f32_16x16x32_f16 v[82:85], v[58:61], v[66:69], v[90:93]
	v_mfma_f32_16x16x32_f16 v[78:81], v[50:53], v[200:203], v[78:81]
	v_mfma_f32_16x16x32_f16 v[74:77], v[58:61], v[200:203], v[74:77]
	v_mfma_f32_16x16x32_f16 v[46:49], v[50:53], v[214:217], v[46:49]
	v_mfma_f32_16x16x32_f16 v[42:45], v[58:61], v[214:217], v[42:45]
	v_mfma_f32_16x16x32_f16 v[14:17], v[50:53], v[222:225], v[14:17]
	v_mfma_f32_16x16x32_f16 v[10:13], v[58:61], v[222:225], v[10:13]
	v_mfma_f32_16x16x32_f16 v[90:93], v[62:65], v[70:73], v[82:85]
	v_mfma_f32_16x16x32_f16 v[78:81], v[54:57], v[204:207], v[78:81]
	v_mfma_f32_16x16x32_f16 v[74:77], v[62:65], v[204:207], v[74:77]
	v_mfma_f32_16x16x32_f16 v[46:49], v[54:57], v[218:221], v[46:49]
	v_mfma_f32_16x16x32_f16 v[42:45], v[62:65], v[218:221], v[42:45]
	v_mfma_f32_16x16x32_f16 v[14:17], v[54:57], v[230:233], v[14:17]
	v_mfma_f32_16x16x32_f16 v[10:13], v[62:65], v[230:233], v[10:13]
	v_mfma_f32_16x16x32_f16 v[18:21], v[172:175], v[66:69], v[18:21]
	v_mfma_f32_16x16x32_f16 v[86:89], v[176:179], v[70:73], v[18:21]
	v_mfma_f32_16x16x32_f16 v[18:21], v[192:195], v[66:69], v[22:25]
	v_mfma_f32_16x16x32_f16 v[82:85], v[196:199], v[70:73], v[18:21]
	v_mfma_f32_16x16x32_f16 v[18:21], v[172:175], v[200:203], v[26:29]
	v_mfma_f32_16x16x32_f16 v[70:73], v[176:179], v[204:207], v[18:21]
	v_mfma_f32_16x16x32_f16 v[18:21], v[192:195], v[200:203], v[30:33]
	v_mfma_f32_16x16x32_f16 v[66:69], v[196:199], v[204:207], v[18:21]
	v_mfma_f32_16x16x32_f16 v[18:21], v[172:175], v[214:217], v[38:41]
	v_mfma_f32_16x16x32_f16 v[38:41], v[176:179], v[218:221], v[18:21]
	v_mfma_f32_16x16x32_f16 v[18:21], v[192:195], v[214:217], v[34:37]
	v_mfma_f32_16x16x32_f16 v[6:9], v[172:175], v[222:225], v[6:9]
	v_mfma_f32_16x16x32_f16 v[2:5], v[192:195], v[222:225], v[2:5]
	v_mfma_f32_16x16x32_f16 v[34:37], v[196:199], v[218:221], v[18:21]
	v_mfma_f32_16x16x32_f16 v[6:9], v[176:179], v[230:233], v[6:9]
	v_mfma_f32_16x16x32_f16 v[2:5], v[196:199], v[230:233], v[2:5]
	s_barrier
	s_add_i32 s97, s97, 2
	s_add_u32 s2, s2, 0x100
	s_addc_u32 s3, s3, 0
	s_add_u32 s44, s44, 0x100
	s_addc_u32 s45, s45, 0
	s_cmp_gt_u32 s97, 13
	s_cbranch_scc0 .LBB0_452
	s_nop 0
	s_and_b64 vcc, exec, s[14:15]
	s_cbranch_vccz .LBB0_455
	s_barrier

; #define PG8_STAGE(bufoff, gbase) do { _Pragma("unroll") for (int _i = 0; _i < 2; ++_i) \
;         __builtin_amdgcn_global_load_lds((const unsigned*)((const char*)(gbase) + voffA[_i]), (LAS unsigned*)(lds + (bufoff) + ldsw + _i * 8192), 16, 0, 0); } while (0)
; #define PG8_WAIT_V(n) asm volatile("s_waitcnt vmcnt(" #n ")" ::: "memory")
; #define PG8_BAR __builtin_amdgcn_s_barrier()
; template <class Epi, bool ALIGN_EPI, bool SP2, bool BF = false, bool HALFM = false, class Order = StaticOrder>
; __device__ __forceinline__ void gemm_phase(LAS unsigned char* lds, const int tid, const Gemm g, const Order& S, const Epi& E, const bool dry = false) {
;     ...
; #pragma unroll
;     for (int a = 0; a < 2; ++a)
; #pragma unroll
;         for (int b = 0; b < 2; ++b)
; #pragma unroll
;             for (int m = 0; m < 4; ++m)
; #pragma unroll
;                 for (int n = 0; n < 2; ++n) acc[a][b][m][n] = (f32x4){0.f, 0.f, 0.f, 0.f};
;     h16x8 At[4][2], B0[2][2], B1[2][2];
;     const char* cA = (const char*)g.A + (size_t)cur.pm * tstep + (HALFM ? (size_t)cur.hm * hstep : (size_t)0); const char* cB = (const char*)g.Bt + (size_t)cur.pn * tstep;
;     if constexpr (SP2) {
;         PG8_STAGE(PG8_SB(0, 0), cB); PG8_STAGE(PG8_SB(0, 1), cB + hstep); PG8_STAGE(PG8_SA(0, 0), cA); PG8_STAGE(PG8_SA(0, 1), cA + hstep);
;         if (wr == 1) PG8_BAR;
;         PG8_WAIT_V(2); PG8_BAR;
;         PG8_STAGE(PG8_SB(1, 0), cB + kstep); PG8_STAGE(PG8_SA(1, 0), cA + kstep); PG8_STAGE(PG8_SB(1, 1), cB + hstep + kstep);
;         PG8_WAIT_V(6); PG8_BAR;
.LBB0_503:
	v_lshlrev_b32_e32 v10, 2, v131
	s_lshl_b32 s1, s29, 6
	v_lshl_or_b32 v0, v131, 6, v187
	s_lshl_b32 s29, s29, 13
	v_and_b32_e32 v10, 32, v10
	v_bitop3_b32 v11, v0, s29, v10 bitop3:0xde
	s_add_i32 s29, s74, 0x18000
	s_and_b32 s5, s36, 3
	s_add_i32 s36, s29, s6
	v_lshl_add_u64 v[8:9], v[8:9], 0, s[94:95]
	s_mov_b32 m0, s36
	s_add_i32 s37, s36, 0x2000
	s_add_i32 s38, s22, 0x8000
	s_add_i32 s39, s22, 0xa000
	s_waitcnt vmcnt(2)
	s_barrier
	global_load_lds_dwordx4 v[8:9], off
	v_lshl_add_u64 v[6:7], v[6:7], 0, s[94:95]
	s_mov_b32 m0, s37
	s_add_u32 s44, s2, 0x40080
	global_load_lds_dwordx4 v[6:7], off
	v_lshl_add_u64 v[4:5], v[4:5], 0, s[94:95]
	s_mov_b32 m0, s38
	s_addc_u32 s45, s3, 0
	s_add_i32 s42, s74, 0x1c000
	global_load_lds_dwordx4 v[4:5], off
	v_lshl_add_u64 v[2:3], v[2:3], 0, s[94:95]
	s_mov_b32 m0, s39
	s_add_i32 s43, s42, s6
	global_load_lds_dwordx4 v[2:3], off
	v_lshl_add_u64 v[2:3], s[44:45], 0, v[164:165]
	s_mov_b32 m0, s43
	v_readlane_b32 s56, v251, 0
	global_load_lds_dwordx4 v[2:3], off
	v_lshl_add_u64 v[2:3], s[44:45], 0, v[166:167]
	s_add_i32 s44, s43, 0x2000
	s_mov_b32 m0, s44
	s_add_u32 s6, s12, s7
	global_load_lds_dwordx4 v[2:3], off
	v_readlane_b32 s57, v251, 1
	s_addc_u32 s7, s13, 0
	v_readlane_b32 s58, v251, 2
	v_readlane_b32 s59, v251, 3
	s_mov_b64 s[48:49], s[56:57]
	v_lshlrev_b32_e32 v0, 14, v181
	s_add_u32 s45, s48, s6
	v_and_b32_e32 v0, 0xffff8000, v0
	s_addc_u32 s47, s49, s7
	v_lshl_add_u32 v0, v183, 11, v0
	v_and_b32_e32 v2, 1, v181
	v_readlane_b32 s12, v252, 20
	v_lshl_or_b32 v0, v2, 6, v0
	s_add_u32 s6, s12, s6
	v_readlane_b32 s12, v252, 21
	v_lshl_add_u32 v0, v184, 1, v0
	s_addc_u32 s7, s12, s7
	v_lshl_add_u64 v[2:3], s[6:7], 0, v[0:1]
	v_lshlrev_b32_e32 v0, 14, v182
	v_and_b32_e32 v0, 0xffff8000, v0
	v_lshl_add_u32 v0, v185, 11, v0
	v_and_b32_e32 v4, 1, v182
	v_lshl_or_b32 v0, v4, 6, v0
	v_lshl_add_u32 v0, v186, 1, v0
	v_lshl_add_u64 v[4:5], s[6:7], 0, v[0:1]
	s_add_u32 s6, s54, s10
	s_addc_u32 s7, s55, s11
	v_readlane_b32 s10, v253, 0
	v_readlane_b32 s11, v253, 1
	s_add_u32 s6, s10, s6
	s_waitcnt vmcnt(6)
	s_addc_u32 s7, s11, s7
	s_mov_b64 s[50:51], s[58:59]
	s_add_u32 s48, s6, 0x1d00100
	v_mov_b32_e32 v18, 0
	v_lshl_or_b32 v10, s5, 12, v188
	s_addc_u32 s49, s7, 0
	s_mov_b32 s50, -2
	s_mov_b64 s[6:7], 0
	v_add_u32_e32 v0, s74, v11
	v_mov_b32_e32 v19, v18
	v_mov_b32_e32 v20, v18
	v_mov_b32_e32 v21, v18
	s_waitcnt vmcnt(0)
	v_mov_b32_e32 v22, v18
	v_mov_b32_e32 v23, v18
	v_mov_b32_e32 v24, v18
	v_mov_b32_e32 v25, v18
	v_mov_b32_e32 v50, v18
	v_mov_b32_e32 v51, v18
	v_mov_b32_e32 v52, v18
	v_mov_b32_e32 v53, v18
	v_mov_b32_e32 v54, v18
	v_mov_b32_e32 v55, v18
	v_mov_b32_e32 v56, v18
	v_mov_b32_e32 v57, v18
	v_mov_b32_e32 v66, v18
	v_mov_b32_e32 v67, v18
	v_mov_b32_e32 v68, v18
	v_mov_b32_e32 v69, v18
	v_mov_b32_e32 v70, v18
	v_mov_b32_e32 v71, v18
	v_mov_b32_e32 v72, v18
	v_mov_b32_e32 v73, v18
	v_mov_b32_e32 v82, v18
	v_mov_b32_e32 v83, v18
	v_mov_b32_e32 v84, v18
	v_mov_b32_e32 v85, v18
	v_mov_b32_e32 v86, v18
	v_mov_b32_e32 v87, v18
	v_mov_b32_e32 v88, v18
	v_mov_b32_e32 v89, v18
	v_mov_b32_e32 v26, v18
	v_mov_b32_e32 v27, v18
	v_mov_b32_e32 v28, v18
	v_mov_b32_e32 v29, v18
	v_mov_b32_e32 v30, v18
	v_mov_b32_e32 v31, v18
	v_mov_b32_e32 v32, v18
	v_mov_b32_e32 v33, v18
	v_mov_b32_e32 v58, v18
	v_mov_b32_e32 v59, v18
	v_mov_b32_e32 v60, v18
	v_mov_b32_e32 v61, v18
	v_mov_b32_e32 v62, v18
	v_mov_b32_e32 v63, v18
	v_mov_b32_e32 v64, v18
	v_mov_b32_e32 v65, v18
	v_mov_b32_e32 v74, v18
	v_mov_b32_e32 v75, v18
	v_mov_b32_e32 v76, v18
	v_mov_b32_e32 v77, v18
	v_mov_b32_e32 v78, v18
	v_mov_b32_e32 v79, v18
	v_mov_b32_e32 v80, v18
	v_mov_b32_e32 v81, v18
	v_mov_b32_e32 v90, v18
	v_mov_b32_e32 v91, v18
	v_mov_b32_e32 v92, v18
	v_mov_b32_e32 v93, v18
	v_mov_b32_e32 v94, v18
	v_mov_b32_e32 v95, v18
	v_mov_b32_e32 v96, v18
	v_mov_b32_e32 v97, v18
	s_barrier
	v_readlane_b32 s60, v251, 4
	v_readlane_b32 s61, v251, 5
	v_readlane_b32 s62, v251, 6
	v_readlane_b32 s63, v251, 7
	s_nop 0
.LBB0_504:
	v_add_u32_e32 v11, s16, v10
	ds_read_b128 v[6:9], v11
	ds_read_b128 v[12:15], v11 offset:1024
	ds_read_b128 v[34:37], v11 offset:2048
	ds_read_b128 v[38:41], v11 offset:3072
	v_add_u32_e32 v11, s19, v10
	s_add_u32 s10, s45, s6
	ds_read_b128 v[42:45], v11
	ds_read_b128 v[46:49], v11 offset:1024
	ds_read_b128 v[98:101], v11 offset:2048
	ds_read_b128 v[102:105], v11 offset:3072
	s_addc_u32 s11, s47, s7
	s_add_u32 s10, s10, 0x100
	s_addc_u32 s11, s11, 0
	s_add_u32 s51, s48, s6
	s_addc_u32 s52, s49, s7
	s_cmpk_eq_i32 s6, 0x700
	s_cselect_b32 s13, s9, s11
	s_cselect_b32 s12, s8, s10
	s_cselect_b32 s11, s3, s52
	s_cselect_b32 s10, s2, s51
	v_lshl_add_u64 v[16:17], v[2:3], 0, s[6:7]
	s_add_i32 m0, s22, 0xc000
	ds_read_b128 v[106:109], v0
	ds_read_b128 v[110:113], v0 offset:1024
	ds_read_b128 v[114:117], v0 offset:2048
	ds_read_b128 v[118:121], v0 offset:3072
	ds_read_b128 v[122:125], v0 offset:4096
	ds_read_b128 v[126:129], v0 offset:5120
	ds_read_b128 v[132:135], v0 offset:6144
	ds_read_b128 v[136:139], v0 offset:7168
	global_load_lds_dwordx4 v[16:17], off
	v_lshl_add_u64 v[16:17], v[4:5], 0, s[6:7]
	s_add_i32 m0, s22, 0xe000
	s_nop 0
	global_load_lds_dwordx4 v[16:17], off
	s_waitcnt vmcnt(8)
	s_waitcnt lgkmcnt(0)
	s_barrier
; #define PG8_STAGE(bufoff, gbase) do { _Pragma("unroll") for (int _i = 0; _i < 2; ++_i) \
;         __builtin_amdgcn_global_load_lds((const unsigned*)((const char*)(gbase) + voffA[_i]), (LAS unsigned*)(lds + (bufoff) + ldsw + _i * 8192), 16, 0, 0); } while (0)
; #define PG8_LDA(dst, b, h) do { _Pragma("unroll") for (int m = 0; m < 4; ++m) _Pragma("unroll") for (int k = 0; k < 2; ++k) dst[m][k] = *(const LAS h16x8*)(lds + PG8_SA(b, h) + aoff + m * 2048 + k * 1024); } while (0)
; #define PG8_LDB(dst, b, h) do { _Pragma("unroll") for (int n = 0; n < 2; ++n) _Pragma("unroll") for (int k = 0; k < 2; ++k) dst[n][k] = *(const LAS h16x8*)(lds + PG8_SB(b, h) + boff + n * 2048 + k * 1024); } while (0)
; #define PG8_LDA1(dst, b) do { if constexpr (!HALFM) PG8_LDA(dst, b, 1); } while (0)
; #define PG8_MMA1(At, B0, B1) do { if constexpr (!HALFM) { PG8_MMA(1, 0, At, B0); PG8_MMA(1, 1, At, B1); } } while (0)
; #define PG8_WAIT_V(n) asm volatile("s_waitcnt vmcnt(" #n ")" ::: "memory")
; #define PG8_WAIT_L(n) asm volatile("s_waitcnt lgkmcnt(" #n ")" ::: "memory")
; #define PG8_BAR __builtin_amdgcn_s_barrier()
; #define PG8_SCHED __builtin_amdgcn_sched_barrier(0)
; template <class Epi, bool ALIGN_EPI, bool SP2, bool BF = false, bool HALFM = false, class Order = StaticOrder>
; __device__ __forceinline__ void gemm_phase(LAS unsigned char* lds, const int tid, const Gemm g, const Order& S, const Epi& E, const bool dry = false) {
;     ...
;             PG8_WAIT_V(8); PG8_WAIT_L(0); PG8_BAR; PG8_MMA(0, 0, At, B0); PG8_MMA(0, 1, At, B1); PG8_BAR; PG8_SCHED;
;             PG8_LDA1(At, 0); PG8_STAGE(PG8_SB(0, 0), b2); PG8_STAGE(PG8_SB(0, 1), b2 + hstep); PG8_STAGE(PG8_SA(0, 0), a2);
;             PG8_WAIT_V(8); PG8_WAIT_L(0); PG8_BAR; PG8_MMA1(At, B0, B1); PG8_BAR; PG8_SCHED;
;             PG8_LDB(B0, 1, 0); PG8_LDB(B1, 1, 1); PG8_SCHED; PG8_LDA(At, 1, 0); PG8_STAGE(PG8_SA(0, 1), a2 + hstep);
;             PG8_WAIT_V(8); PG8_WAIT_L(0); PG8_BAR; PG8_MMA(0, 0, At, B0); PG8_MMA(0, 1, At, B1); PG8_BAR; PG8_SCHED;
	s_waitcnt lgkmcnt(0)
	v_mfma_f32_16x16x32_f16 v[94:97], v[6:9], v[106:109], v[94:97]
	v_mfma_f32_16x16x32_f16 v[90:93], v[34:37], v[106:109], v[90:93]
	v_mfma_f32_16x16x32_f16 v[78:81], v[6:9], v[114:117], v[78:81]
	v_mfma_f32_16x16x32_f16 v[74:77], v[34:37], v[114:117], v[74:77]
	v_mfma_f32_16x16x32_f16 v[62:65], v[6:9], v[122:125], v[62:65]
	v_mfma_f32_16x16x32_f16 v[58:61], v[34:37], v[122:125], v[58:61]
	v_mfma_f32_16x16x32_f16 v[6:9], v[6:9], v[132:135], v[30:33]
	v_mfma_f32_16x16x32_f16 v[94:97], v[12:15], v[110:113], v[94:97]
	v_mfma_f32_16x16x32_f16 v[90:93], v[38:41], v[110:113], v[90:93]
	v_mfma_f32_16x16x32_f16 v[78:81], v[12:15], v[118:121], v[78:81]
	v_mfma_f32_16x16x32_f16 v[74:77], v[38:41], v[118:121], v[74:77]
	v_mfma_f32_16x16x32_f16 v[62:65], v[12:15], v[126:129], v[62:65]
	v_mfma_f32_16x16x32_f16 v[58:61], v[38:41], v[126:129], v[58:61]
	v_mfma_f32_16x16x32_f16 v[6:9], v[12:15], v[136:139], v[6:9]
	v_mfma_f32_16x16x32_f16 v[12:15], v[34:37], v[132:135], v[26:29]
	v_mfma_f32_16x16x32_f16 v[12:15], v[38:41], v[136:139], v[12:15]
	v_mfma_f32_16x16x32_f16 v[26:29], v[42:45], v[106:109], v[86:89]
	v_mfma_f32_16x16x32_f16 v[34:37], v[46:49], v[110:113], v[26:29]
	v_mfma_f32_16x16x32_f16 v[26:29], v[98:101], v[106:109], v[82:85]
	v_mfma_f32_16x16x32_f16 v[38:41], v[102:105], v[110:113], v[26:29]
	v_mfma_f32_16x16x32_f16 v[26:29], v[42:45], v[114:117], v[70:73]
	v_mfma_f32_16x16x32_f16 v[70:73], v[46:49], v[118:121], v[26:29]
	v_mfma_f32_16x16x32_f16 v[26:29], v[98:101], v[114:117], v[66:69]
	v_mfma_f32_16x16x32_f16 v[66:69], v[102:105], v[118:121], v[26:29]
	v_mfma_f32_16x16x32_f16 v[26:29], v[42:45], v[122:125], v[54:57]
	v_mfma_f32_16x16x32_f16 v[54:57], v[46:49], v[126:129], v[26:29]
	v_mfma_f32_16x16x32_f16 v[26:29], v[98:101], v[122:125], v[50:53]
	v_mfma_f32_16x16x32_f16 v[22:25], v[42:45], v[132:135], v[22:25]
	v_mfma_f32_16x16x32_f16 v[16:19], v[98:101], v[132:135], v[18:21]
	v_mfma_f32_16x16x32_f16 v[50:53], v[102:105], v[126:129], v[26:29]
	v_mfma_f32_16x16x32_f16 v[22:25], v[46:49], v[136:139], v[22:25]
	v_mfma_f32_16x16x32_f16 v[16:19], v[102:105], v[136:139], v[16:19]
	s_barrier
	s_mov_b32 m0, s17
	v_lshl_add_u64 v[144:145], s[10:11], 0, v[164:165]
	s_add_u32 s52, s10, 0x40000
	global_load_lds_dwordx4 v[144:145], off
	v_lshl_add_u64 v[146:147], s[10:11], 0, v[166:167]
	s_mov_b32 m0, s18
	s_addc_u32 s53, s11, 0
	global_load_lds_dwordx4 v[146:147], off
	v_lshl_add_u64 v[20:21], s[52:53], 0, v[164:165]
	s_mov_b32 m0, s20
	v_lshl_add_u64 v[148:149], s[12:13], 0, v[164:165]
	global_load_lds_dwordx4 v[20:21], off
	v_lshl_add_u64 v[20:21], s[52:53], 0, v[166:167]
	s_mov_b32 m0, s21
	v_lshl_add_u64 v[150:151], s[12:13], 0, v[166:167]
	global_load_lds_dwordx4 v[20:21], off
	s_mov_b32 m0, s22
	s_nop 0
	global_load_lds_dwordx4 v[148:149], off
	s_mov_b32 m0, s23
	s_nop 0
	global_load_lds_dwordx4 v[150:151], off
	s_waitcnt vmcnt(8)
	s_waitcnt lgkmcnt(0)
	s_barrier
	s_barrier
	v_add_u32_e32 v11, s29, v10
	ds_read_b128 v[26:29], v11
	ds_read_b128 v[30:33], v11 offset:1024
	ds_read_b128 v[42:45], v11 offset:2048
	ds_read_b128 v[46:49], v11 offset:3072
	v_add_u32_e32 v11, s42, v10
	ds_read_b128 v[98:101], v11
	ds_read_b128 v[102:105], v11 offset:1024
	ds_read_b128 v[106:109], v11 offset:2048
	ds_read_b128 v[110:113], v11 offset:3072
	s_add_u32 s12, s12, 0x40000
	s_addc_u32 s13, s13, 0
	s_mov_b32 m0, s24
	v_lshl_add_u64 v[20:21], s[12:13], 0, v[164:165]
	ds_read_b128 v[82:85], v0 offset:32768
	ds_read_b128 v[114:117], v0 offset:33792
	ds_read_b128 v[118:121], v0 offset:34816
	ds_read_b128 v[122:125], v0 offset:35840
	ds_read_b128 v[126:129], v0 offset:36864
	ds_read_b128 v[132:135], v0 offset:37888
	ds_read_b128 v[136:139], v0 offset:38912
	ds_read_b128 v[140:143], v0 offset:39936
	global_load_lds_dwordx4 v[20:21], off
	v_lshl_add_u64 v[20:21], s[12:13], 0, v[166:167]
	s_mov_b32 m0, s25
	s_nop 0
	global_load_lds_dwordx4 v[20:21], off
	s_waitcnt vmcnt(8)
	s_waitcnt lgkmcnt(0)
	s_barrier
; #define PG8_STAGE(bufoff, gbase) do { _Pragma("unroll") for (int _i = 0; _i < 2; ++_i) \
;         __builtin_amdgcn_global_load_lds((const unsigned*)((const char*)(gbase) + voffA[_i]), (LAS unsigned*)(lds + (bufoff) + ldsw + _i * 8192), 16, 0, 0); } while (0)
; #define PG8_LDA1(dst, b) do { if constexpr (!HALFM) PG8_LDA(dst, b, 1); } while (0)
; #define PG8_MMA1(At, B0, B1) do { if constexpr (!HALFM) { PG8_MMA(1, 0, At, B0); PG8_MMA(1, 1, At, B1); } } while (0)
; #define PG8_WAIT_V(n) asm volatile("s_waitcnt vmcnt(" #n ")" ::: "memory")
; #define PG8_WAIT_L(n) asm volatile("s_waitcnt lgkmcnt(" #n ")" ::: "memory")
; #define PG8_BAR __builtin_amdgcn_s_barrier()
; #define PG8_SCHED __builtin_amdgcn_sched_barrier(0)
; template <class Epi, bool ALIGN_EPI, bool SP2, bool BF = false, bool HALFM = false, class Order = StaticOrder>
; __device__ __forceinline__ void gemm_phase(LAS unsigned char* lds, const int tid, const Gemm g, const Order& S, const Epi& E, const bool dry = false) {
;     ...
;             PG8_WAIT_V(8); PG8_WAIT_L(0); PG8_BAR; PG8_MMA(0, 0, At, B0); PG8_MMA(0, 1, At, B1); PG8_BAR; PG8_SCHED;
;             PG8_LDA1(At, 1); PG8_STAGE(PG8_SB(1, 0), b3); PG8_STAGE(PG8_SB(1, 1), b3 + hstep); PG8_STAGE(PG8_SA(1, 0), a3);
;             PG8_WAIT_V(8); PG8_WAIT_L(0); PG8_BAR; PG8_MMA1(At, B0, B1); PG8_BAR; PG8_SCHED;
;     ...
;         if constexpr (ALIGN_EPI) { if (wr == 0) PG8_BAR; }
	s_waitcnt lgkmcnt(0)
	v_mfma_f32_16x16x32_f16 v[86:89], v[26:29], v[82:85], v[94:97]
	v_mfma_f32_16x16x32_f16 v[78:81], v[26:29], v[118:121], v[78:81]
	v_mfma_f32_16x16x32_f16 v[62:65], v[26:29], v[126:129], v[62:65]
	v_mfma_f32_16x16x32_f16 v[6:9], v[26:29], v[136:139], v[6:9]
	v_mfma_f32_16x16x32_f16 v[94:97], v[30:33], v[114:117], v[86:89]
	v_mfma_f32_16x16x32_f16 v[86:89], v[42:45], v[82:85], v[90:93]
	v_mfma_f32_16x16x32_f16 v[78:81], v[30:33], v[122:125], v[78:81]
	v_mfma_f32_16x16x32_f16 v[74:77], v[42:45], v[118:121], v[74:77]
	v_mfma_f32_16x16x32_f16 v[62:65], v[30:33], v[132:135], v[62:65]
	v_mfma_f32_16x16x32_f16 v[58:61], v[42:45], v[126:129], v[58:61]
	v_mfma_f32_16x16x32_f16 v[30:33], v[30:33], v[140:143], v[6:9]
	v_mfma_f32_16x16x32_f16 v[6:9], v[42:45], v[136:139], v[12:15]
	v_mfma_f32_16x16x32_f16 v[90:93], v[46:49], v[114:117], v[86:89]
	v_mfma_f32_16x16x32_f16 v[74:77], v[46:49], v[122:125], v[74:77]
	v_mfma_f32_16x16x32_f16 v[58:61], v[46:49], v[132:135], v[58:61]
	v_mfma_f32_16x16x32_f16 v[26:29], v[46:49], v[140:143], v[6:9]
	v_mfma_f32_16x16x32_f16 v[6:9], v[98:101], v[82:85], v[34:37]
	v_mfma_f32_16x16x32_f16 v[86:89], v[102:105], v[114:117], v[6:9]
	v_mfma_f32_16x16x32_f16 v[6:9], v[106:109], v[82:85], v[38:41]
	v_mfma_f32_16x16x32_f16 v[82:85], v[110:113], v[114:117], v[6:9]
	v_mfma_f32_16x16x32_f16 v[6:9], v[98:101], v[118:121], v[70:73]
	v_mfma_f32_16x16x32_f16 v[70:73], v[102:105], v[122:125], v[6:9]
	v_mfma_f32_16x16x32_f16 v[6:9], v[106:109], v[118:121], v[66:69]
	v_mfma_f32_16x16x32_f16 v[66:69], v[110:113], v[122:125], v[6:9]
	v_mfma_f32_16x16x32_f16 v[6:9], v[98:101], v[126:129], v[54:57]
	v_mfma_f32_16x16x32_f16 v[54:57], v[102:105], v[132:135], v[6:9]
	v_mfma_f32_16x16x32_f16 v[6:9], v[106:109], v[126:129], v[50:53]
	v_mfma_f32_16x16x32_f16 v[50:53], v[110:113], v[132:135], v[6:9]
	v_mfma_f32_16x16x32_f16 v[6:9], v[98:101], v[136:139], v[22:25]
	v_mfma_f32_16x16x32_f16 v[22:25], v[102:105], v[140:143], v[6:9]
	v_mfma_f32_16x16x32_f16 v[6:9], v[106:109], v[136:139], v[16:19]
	v_mfma_f32_16x16x32_f16 v[18:21], v[110:113], v[140:143], v[6:9]
	s_barrier
	s_mov_b32 m0, s36
	s_nop 3
	v_lshl_add_u64 v[6:7], v[144:145], 0, s[94:95]
	s_add_u32 s10, s10, 0x40080
	global_load_lds_dwordx4 v[6:7], off
	v_lshl_add_u64 v[6:7], v[146:147], 0, s[94:95]
	s_mov_b32 m0, s37
	s_addc_u32 s11, s11, 0
	global_load_lds_dwordx4 v[6:7], off
	v_lshl_add_u64 v[6:7], s[10:11], 0, v[164:165]
	s_mov_b32 m0, s43
	s_nop 0
	global_load_lds_dwordx4 v[6:7], off
	v_lshl_add_u64 v[6:7], s[10:11], 0, v[166:167]
	s_mov_b32 m0, s44
	s_nop 0
	global_load_lds_dwordx4 v[6:7], off
	v_lshl_add_u64 v[6:7], v[148:149], 0, s[94:95]
	s_mov_b32 m0, s38
	s_nop 0
	global_load_lds_dwordx4 v[6:7], off
	v_lshl_add_u64 v[6:7], v[150:151], 0, s[94:95]
	s_mov_b32 m0, s39
	s_nop 0
	global_load_lds_dwordx4 v[6:7], off
	s_waitcnt vmcnt(8)
	s_waitcnt lgkmcnt(0)
	s_barrier
	s_barrier
	s_add_i32 s50, s50, 2
	s_add_u32 s6, s6, 0x100
	s_addc_u32 s7, s7, 0
	s_cmp_gt_u32 s50, 13
	s_cbranch_scc0 .LBB0_504
	s_nop 0
	s_cmpk_lt_u32 s15, 0x100
	s_mov_b64 s[60:61], 0x800
	s_cbranch_scc0 .LBB0_507
	s_barrier

; template <class Epi, bool ALIGN_EPI, bool SP2, bool BF = false, bool HALFM = false, class Order = StaticOrder>
; __device__ __forceinline__ void gemm_phase(LAS unsigned char* lds, const int tid, const Gemm g, const Order& S, const Epi& E, const bool dry = false) {
;     ...
;     f32x4 acc[2][2][4][2];
; #pragma unroll
;     for (int a = 0; a < 2; ++a)
; #pragma unroll
;         for (int b = 0; b < 2; ++b)
; #pragma unroll
;             for (int m = 0; m < 4; ++m)
; #pragma unroll
;                 for (int n = 0; n < 2; ++n) acc[a][b][m][n] = (f32x4){0.f, 0.f, 0.f, 0.f};
.Lpf_noshw:
	s_cmp_lg_u32 s100, 0
	s_cbranch_scc1 .Lin_peel
	v_mov_b32_e32 v58, 0
	v_mov_b32_e32 v59, v58
	v_mov_b32_e32 v60, v58
	v_mov_b32_e32 v61, v58
	v_mov_b32_e32 v62, v58
	v_mov_b32_e32 v63, v58
	v_mov_b32_e32 v64, v58
	v_mov_b32_e32 v65, v58
	v_mov_b32_e32 v74, v58
	v_mov_b32_e32 v75, v58
	v_mov_b32_e32 v76, v58
	v_mov_b32_e32 v77, v58
	v_mov_b32_e32 v78, v58
	v_mov_b32_e32 v79, v58
	v_mov_b32_e32 v80, v58
	v_mov_b32_e32 v81, v58
	v_mov_b32_e32 v82, v58
	v_mov_b32_e32 v83, v58
	v_mov_b32_e32 v84, v58
	v_mov_b32_e32 v85, v58
	v_mov_b32_e32 v86, v58
	v_mov_b32_e32 v87, v58
	v_mov_b32_e32 v88, v58
	v_mov_b32_e32 v89, v58
	v_mov_b32_e32 v90, v58
	v_mov_b32_e32 v91, v58
	v_mov_b32_e32 v92, v58
	v_mov_b32_e32 v93, v58
	v_mov_b32_e32 v94, v58
	v_mov_b32_e32 v95, v58
	v_mov_b32_e32 v96, v58
	v_mov_b32_e32 v97, v58
	v_mov_b32_e32 v2, v58
	v_mov_b32_e32 v3, v58
	v_mov_b32_e32 v4, v58
	v_mov_b32_e32 v5, v58
	v_mov_b32_e32 v6, v58
	v_mov_b32_e32 v7, v58
	v_mov_b32_e32 v8, v58
	v_mov_b32_e32 v9, v58
	v_mov_b32_e32 v10, v58
	v_mov_b32_e32 v11, v58
	v_mov_b32_e32 v12, v58
	v_mov_b32_e32 v13, v58
	v_mov_b32_e32 v14, v58
	v_mov_b32_e32 v15, v58
	v_mov_b32_e32 v16, v58
	v_mov_b32_e32 v17, v58
	v_mov_b32_e32 v18, v58
	v_mov_b32_e32 v19, v58
	v_mov_b32_e32 v20, v58
	v_mov_b32_e32 v21, v58
	v_mov_b32_e32 v22, v58
	v_mov_b32_e32 v23, v58
	v_mov_b32_e32 v24, v58
	v_mov_b32_e32 v25, v58
	v_mov_b32_e32 v26, v58
	v_mov_b32_e32 v27, v58
	v_mov_b32_e32 v28, v58
	v_mov_b32_e32 v29, v58
	v_mov_b32_e32 v30, v58
	v_mov_b32_e32 v31, v58
	v_mov_b32_e32 v32, v58
	v_mov_b32_e32 v33, v58
	v_mov_b32_e32 v98, v58
	v_mov_b32_e32 v99, v58
	v_mov_b32_e32 v100, v58
	v_mov_b32_e32 v101, v58
	v_mov_b32_e32 v102, v58
	v_mov_b32_e32 v103, v58
	v_mov_b32_e32 v104, v58
	v_mov_b32_e32 v105, v58
	v_mov_b32_e32 v106, v58
	v_mov_b32_e32 v107, v58
	v_mov_b32_e32 v108, v58
	v_mov_b32_e32 v109, v58
	v_mov_b32_e32 v110, v58
	v_mov_b32_e32 v111, v58
	v_mov_b32_e32 v112, v58
	v_mov_b32_e32 v113, v58
	v_mov_b32_e32 v114, v58
	v_mov_b32_e32 v115, v58
	v_mov_b32_e32 v116, v58
	v_mov_b32_e32 v117, v58
	v_mov_b32_e32 v118, v58
	v_mov_b32_e32 v119, v58
	v_mov_b32_e32 v120, v58
	v_mov_b32_e32 v121, v58
	v_mov_b32_e32 v122, v58
	v_mov_b32_e32 v123, v58
	v_mov_b32_e32 v124, v58
	v_mov_b32_e32 v125, v58
	v_mov_b32_e32 v126, v58
	v_mov_b32_e32 v127, v58
	v_mov_b32_e32 v128, v58
	v_mov_b32_e32 v129, v58
	v_mov_b32_e32 v34, v58
	v_mov_b32_e32 v35, v58
	v_mov_b32_e32 v36, v58
	v_mov_b32_e32 v37, v58
	v_mov_b32_e32 v38, v58
	v_mov_b32_e32 v39, v58
	v_mov_b32_e32 v40, v58
	v_mov_b32_e32 v41, v58
	v_mov_b32_e32 v42, v58
	v_mov_b32_e32 v43, v58
	v_mov_b32_e32 v44, v58
	v_mov_b32_e32 v45, v58
	v_mov_b32_e32 v54, v58
	v_mov_b32_e32 v55, v58
	v_mov_b32_e32 v56, v58
	v_mov_b32_e32 v57, v58
	v_mov_b32_e32 v46, v58
	v_mov_b32_e32 v47, v58
	v_mov_b32_e32 v48, v58
	v_mov_b32_e32 v49, v58
	v_mov_b32_e32 v50, v58
	v_mov_b32_e32 v51, v58
	v_mov_b32_e32 v52, v58
	v_mov_b32_e32 v53, v58
	v_mov_b32_e32 v66, v58
	v_mov_b32_e32 v67, v58
	v_mov_b32_e32 v68, v58
	v_mov_b32_e32 v69, v58
	v_mov_b32_e32 v70, v58
	v_mov_b32_e32 v71, v58
	v_mov_b32_e32 v72, v58
	v_mov_b32_e32 v73, v58
	s_nop 0

; #define PG8_STAGE(bufoff, gbase) do { _Pragma("unroll") for (int _i = 0; _i < 2; ++_i) \
;         __builtin_amdgcn_global_load_lds((const unsigned*)((const char*)(gbase) + voffA[_i]), (LAS unsigned*)(lds + (bufoff) + ldsw + _i * 8192), 16, 0, 0); } while (0)
; #define PG8_LDA1(dst, b) do { if constexpr (!HALFM) PG8_LDA(dst, b, 1); } while (0)
; #define PG8_MMA1(At, B0, B1) do { if constexpr (!HALFM) { PG8_MMA(1, 0, At, B0); PG8_MMA(1, 1, At, B1); } } while (0)
; #define PG8_WAIT_V(n) asm volatile("s_waitcnt vmcnt(" #n ")" ::: "memory")
; #define PG8_WAIT_L(n) asm volatile("s_waitcnt lgkmcnt(" #n ")" ::: "memory")
; #define PG8_BAR __builtin_amdgcn_s_barrier()
; #define PG8_SCHED __builtin_amdgcn_sched_barrier(0)
; template <class Epi, bool ALIGN_EPI, bool SP2, bool BF = false, bool HALFM = false, class Order = StaticOrder>
; __device__ __forceinline__ void gemm_phase(LAS unsigned char* lds, const int tid, const Gemm g, const Order& S, const Epi& E, const bool dry = false) {
;     ...
;         for (int t = 0; t < nt; t += 2) {
;     ...
;             PG8_LDA1(At, 1); PG8_STAGE(PG8_SB(1, 0), b3); PG8_STAGE(PG8_SB(1, 1), b3 + hstep); PG8_STAGE(PG8_SA(1, 0), a3);
;             PG8_WAIT_V(8); PG8_WAIT_L(0); PG8_BAR; PG8_MMA1(At, B0, B1); PG8_BAR; PG8_SCHED;
.Lin_seg4:
	s_mov_b32 m0, s80
	s_add_u32 vcc_lo, s38, 0x80
	s_addc_u32 vcc_hi, s39, 0
	s_add_u32 s38, s38, 0x40080
	ds_read_b128 v[170:173], v199 offset:49152
	ds_read_b128 v[174:177], v199 offset:50176
	ds_read_b128 v[178:181], v199 offset:51200
	ds_read_b128 v[182:185], v199 offset:52224
	ds_read_b128 v[186:189], v199 offset:53248
	ds_read_b128 v[190:193], v199 offset:54272
	ds_read_b128 v[200:203], v199 offset:55296
	ds_read_b128 v[204:207], v199 offset:56320
	global_load_lds_dwordx4 v0, vcc
	s_nop 0
	s_mov_b32 m0, s81
	s_addc_u32 s39, s39, 0
	global_load_lds_dwordx4 v164, vcc
	s_nop 0
	s_mov_b32 m0, s85
	s_nop 0
	global_load_lds_dwordx4 v0, s[38:39]
	s_nop 0
	s_mov_b32 m0, s86
	s_nop 0
	global_load_lds_dwordx4 v164, s[38:39]
	s_add_u32 vcc_lo, s42, 0xfffc0080
	s_addc_u32 vcc_hi, s43, -1
	s_mov_b32 m0, s82
	s_nop 0
	global_load_lds_dwordx4 v0, vcc
	s_nop 0
	s_mov_b32 m0, s83
	s_nop 0
	global_load_lds_dwordx4 v164, vcc
	s_waitcnt vmcnt(8)
	s_waitcnt lgkmcnt(0)
	s_barrier
	s_waitcnt lgkmcnt(0)
	v_mfma_f32_16x16x32_f16 v[30:33], v[132:135], v[170:173], v[30:33]
	v_mfma_f32_16x16x32_f16 v[26:29], v[140:143], v[170:173], v[26:29]
	v_mfma_f32_16x16x32_f16 v[22:25], v[132:135], v[178:181], v[22:25]
	v_mfma_f32_16x16x32_f16 v[18:21], v[140:143], v[178:181], v[18:21]
	v_mfma_f32_16x16x32_f16 v[14:17], v[132:135], v[186:189], v[14:17]
	v_mfma_f32_16x16x32_f16 v[10:13], v[140:143], v[186:189], v[10:13]
	v_mfma_f32_16x16x32_f16 v[6:9], v[132:135], v[200:203], v[6:9]
	v_mfma_f32_16x16x32_f16 v[2:5], v[140:143], v[200:203], v[2:5]
	v_mfma_f32_16x16x32_f16 v[30:33], v[136:139], v[174:177], v[30:33]
	v_mfma_f32_16x16x32_f16 v[26:29], v[144:147], v[174:177], v[26:29]
	v_mfma_f32_16x16x32_f16 v[22:25], v[136:139], v[182:185], v[22:25]
	v_mfma_f32_16x16x32_f16 v[18:21], v[144:147], v[182:185], v[18:21]
	v_mfma_f32_16x16x32_f16 v[14:17], v[136:139], v[190:193], v[14:17]
	v_mfma_f32_16x16x32_f16 v[10:13], v[144:147], v[190:193], v[10:13]
	v_mfma_f32_16x16x32_f16 v[6:9], v[136:139], v[204:207], v[6:9]
	v_mfma_f32_16x16x32_f16 v[2:5], v[144:147], v[204:207], v[2:5]
	v_mfma_f32_16x16x32_f16 v[94:97], v[148:151], v[170:173], v[94:97]
	v_mfma_f32_16x16x32_f16 v[90:93], v[156:159], v[170:173], v[90:93]
	v_mfma_f32_16x16x32_f16 v[86:89], v[148:151], v[178:181], v[86:89]
	v_mfma_f32_16x16x32_f16 v[82:85], v[156:159], v[178:181], v[82:85]
	v_mfma_f32_16x16x32_f16 v[78:81], v[148:151], v[186:189], v[78:81]
	v_mfma_f32_16x16x32_f16 v[74:77], v[156:159], v[186:189], v[74:77]
	v_mfma_f32_16x16x32_f16 v[62:65], v[148:151], v[200:203], v[62:65]
	v_mfma_f32_16x16x32_f16 v[58:61], v[156:159], v[200:203], v[58:61]
	v_mfma_f32_16x16x32_f16 v[94:97], v[152:155], v[174:177], v[94:97]
	v_mfma_f32_16x16x32_f16 v[90:93], v[160:163], v[174:177], v[90:93]
	v_mfma_f32_16x16x32_f16 v[86:89], v[152:155], v[182:185], v[86:89]
	v_mfma_f32_16x16x32_f16 v[82:85], v[160:163], v[182:185], v[82:85]
	v_mfma_f32_16x16x32_f16 v[78:81], v[152:155], v[190:193], v[78:81]
	v_mfma_f32_16x16x32_f16 v[74:77], v[160:163], v[190:193], v[74:77]
	v_mfma_f32_16x16x32_f16 v[62:65], v[152:155], v[204:207], v[62:65]
	v_mfma_f32_16x16x32_f16 v[58:61], v[160:163], v[204:207], v[58:61]
	s_barrier
	s_add_i32 s21, s21, 2
	s_add_u32 s11, s11, 0x100
	s_addc_u32 s19, s19, 0
	s_add_u32 s36, s36, 0x100
	s_addc_u32 s37, s37, 0
	s_cmp_gt_u32 s21, 13
	s_cbranch_scc0 .LBB0_561
	s_nop 0
	s_and_b64 vcc, exec, s[12:13]
	s_cbranch_vccz .LBB0_564
	s_barrier
